# first barrier on the same fast protocol; 4-deep pipelined counter polls into spare VGPRs (v248-251), no drain after release
# speedup vs baseline: 1.5431x; 1.0030x over previous
.LBB0_373:
	v_mov_b32_e32 v1, v0
	s_and_b32 s0, s11, 0xffffffc0
	s_and_b32 s13, s7, 0x380
	s_ashr_i32 s1, s0, 31
	v_and_b32_e32 v2, 0x7f, v1
	v_ashrrev_i32_e32 v7, 7, v1
	v_add_u32_e32 v5, 0x200, v1
	v_add_u32_e32 v6, 0x400, v1
	v_add_u32_e32 v8, 0x600, v1
	v_add_u32_e32 v9, 0x800, v1
	v_add_u32_e32 v10, 0xa00, v1
	v_add_u32_e32 v11, 0xc00, v1
	v_add_u32_e32 v12, 0xe00, v1
	v_add_u32_e32 v13, 0x1000, v1
	v_add_u32_e32 v14, 0x1200, v1
	v_add_u32_e32 v15, 0x1400, v1
	v_add_u32_e32 v16, 0x1600, v1
	v_add_u32_e32 v17, 0x1800, v1
	v_add_u32_e32 v18, 0x1a00, v1
	v_add_u32_e32 v19, 0x1c00, v1
	v_add_u32_e32 v20, 0x1e00, v1
	v_or_b32_e32 v22, s13, v2
	v_add_u32_e32 v4, s0, v7
	v_ashrrev_i32_e32 v41, 7, v5
	v_ashrrev_i32_e32 v42, 7, v6
	v_ashrrev_i32_e32 v43, 7, v8
	v_ashrrev_i32_e32 v9, 7, v9
	v_ashrrev_i32_e32 v44, 7, v10
	v_ashrrev_i32_e32 v45, 7, v11
	v_ashrrev_i32_e32 v46, 7, v12
	v_ashrrev_i32_e32 v47, 7, v13
	v_ashrrev_i32_e32 v48, 7, v14
	v_ashrrev_i32_e32 v49, 7, v15
	v_ashrrev_i32_e32 v50, 7, v16
	v_ashrrev_i32_e32 v51, 7, v17
	v_ashrrev_i32_e32 v52, 7, v18
	v_ashrrev_i32_e32 v53, 7, v19
	v_ashrrev_i32_e32 v54, 7, v20
	v_ashrrev_i32_e32 v21, 3, v1
	v_lshl_add_u32 v6, v2, 2, 32
	v_ashrrev_i32_e32 v5, 31, v4
	v_lshlrev_b32_e32 v2, 2, v22
	v_add_u32_e32 v10, s0, v41
	v_add_u32_e32 v12, s0, v42
	v_add_u32_e32 v14, s0, v43
	v_add_u32_e32 v16, s0, v9
	v_add_u32_e32 v18, s0, v44
	v_add_u32_e32 v20, s0, v45
	v_add_u32_e32 v22, s0, v46
	v_add_u32_e32 v24, s0, v47
	v_add_u32_e32 v26, s0, v48
	v_add_u32_e32 v28, s0, v49
	v_add_u32_e32 v30, s0, v50
	v_add_u32_e32 v32, s0, v51
	v_add_u32_e32 v34, s0, v52
	v_add_u32_e32 v36, s0, v53
	v_add_u32_e32 v38, s0, v54
	v_lshlrev_b32_e32 v55, 2, v21
	v_add_u32_e32 v8, s13, v21
	v_lshlrev_b64 v[4:5], 12, v[4:5]
	v_ashrrev_i32_e32 v11, 31, v10
	v_ashrrev_i32_e32 v13, 31, v12
	v_ashrrev_i32_e32 v15, 31, v14
	v_ashrrev_i32_e32 v17, 31, v16
	v_ashrrev_i32_e32 v19, 31, v18
	v_ashrrev_i32_e32 v21, 31, v20
	v_ashrrev_i32_e32 v23, 31, v22
	v_ashrrev_i32_e32 v25, 31, v24
	v_ashrrev_i32_e32 v27, 31, v26
	v_ashrrev_i32_e32 v29, 31, v28
	v_ashrrev_i32_e32 v31, 31, v30
	v_ashrrev_i32_e32 v33, 31, v32
	v_ashrrev_i32_e32 v35, 31, v34
	v_ashrrev_i32_e32 v37, 31, v36
	v_ashrrev_i32_e32 v39, 31, v38
	v_lshl_add_u64 v[4:5], s[94:95], 0, v[4:5]
	v_lshlrev_b64 v[10:11], 12, v[10:11]
	v_lshlrev_b64 v[12:13], 12, v[12:13]
	v_lshlrev_b64 v[14:15], 12, v[14:15]
	v_lshlrev_b64 v[16:17], 12, v[16:17]
	v_lshlrev_b64 v[18:19], 12, v[18:19]
	v_lshlrev_b64 v[20:21], 12, v[20:21]
	v_lshlrev_b64 v[22:23], 12, v[22:23]
	v_lshlrev_b64 v[24:25], 12, v[24:25]
	v_lshlrev_b64 v[26:27], 12, v[26:27]
	v_lshlrev_b64 v[28:29], 12, v[28:29]
	v_lshlrev_b64 v[30:31], 12, v[30:31]
	v_lshlrev_b64 v[32:33], 12, v[32:33]
	v_lshlrev_b64 v[34:35], 12, v[34:35]
	v_lshlrev_b64 v[36:37], 12, v[36:37]
	v_lshlrev_b64 v[38:39], 12, v[38:39]
	v_lshl_add_u64 v[4:5], v[4:5], 0, v[2:3]
	v_lshl_add_u64 v[10:11], s[94:95], 0, v[10:11]
	v_lshl_add_u64 v[12:13], s[94:95], 0, v[12:13]
	v_lshl_add_u64 v[14:15], s[94:95], 0, v[14:15]
	v_lshl_add_u64 v[16:17], s[94:95], 0, v[16:17]
	v_lshl_add_u64 v[18:19], s[94:95], 0, v[18:19]
	v_lshl_add_u64 v[20:21], s[94:95], 0, v[20:21]
	v_lshl_add_u64 v[22:23], s[94:95], 0, v[22:23]
	v_lshl_add_u64 v[24:25], s[94:95], 0, v[24:25]
	v_lshl_add_u64 v[26:27], s[94:95], 0, v[26:27]
	v_lshl_add_u64 v[28:29], s[94:95], 0, v[28:29]
	v_lshl_add_u64 v[30:31], s[94:95], 0, v[30:31]
	v_lshl_add_u64 v[32:33], s[94:95], 0, v[32:33]
	v_lshl_add_u64 v[34:35], s[94:95], 0, v[34:35]
	v_lshl_add_u64 v[36:37], s[94:95], 0, v[36:37]
	v_lshl_add_u64 v[38:39], s[94:95], 0, v[38:39]
	v_lshl_add_u64 v[10:11], v[10:11], 0, v[2:3]
	v_lshl_add_u64 v[12:13], v[12:13], 0, v[2:3]
	v_lshl_add_u64 v[14:15], v[14:15], 0, v[2:3]
	v_lshl_add_u64 v[16:17], v[16:17], 0, v[2:3]
	v_lshl_add_u64 v[18:19], v[18:19], 0, v[2:3]
	v_lshl_add_u64 v[20:21], v[20:21], 0, v[2:3]
	v_lshl_add_u64 v[22:23], v[22:23], 0, v[2:3]
	v_lshl_add_u64 v[24:25], v[24:25], 0, v[2:3]
	v_lshl_add_u64 v[26:27], v[26:27], 0, v[2:3]
	v_lshl_add_u64 v[28:29], v[28:29], 0, v[2:3]
	v_lshl_add_u64 v[30:31], v[30:31], 0, v[2:3]
	v_lshl_add_u64 v[32:33], v[32:33], 0, v[2:3]
	v_lshl_add_u64 v[34:35], v[34:35], 0, v[2:3]
	v_lshl_add_u64 v[36:37], v[36:37], 0, v[2:3]
	v_lshl_add_u64 v[38:39], v[38:39], 0, v[2:3]
	global_load_dword v56, v[4:5], off nt
	global_load_dword v57, v[10:11], off nt
	global_load_dword v58, v[12:13], off nt
	global_load_dword v59, v[14:15], off nt
	global_load_dword v60, v[16:17], off nt
	global_load_dword v61, v[18:19], off nt
	global_load_dword v62, v[20:21], off nt
	global_load_dword v63, v[22:23], off nt
	global_load_dword v64, v[24:25], off nt
	global_load_dword v65, v[26:27], off nt
	global_load_dword v66, v[28:29], off nt
	global_load_dword v67, v[30:31], off nt
	global_load_dword v68, v[32:33], off nt
	global_load_dword v69, v[34:35], off nt
	global_load_dword v70, v[36:37], off nt
	global_load_dword v71, v[38:39], off nt
	v_lshlrev_b32_e32 v1, 3, v1
	v_and_b32_e32 v1, 56, v1
	s_lshl_b64 s[2:3], s[0:1], 1
	v_mad_u64_u32 v[12:13], s[0:1], v42, s10, v[6:7]
	v_mul_u32_u24_e32 v2, 0x204, v1
	v_mad_u64_u32 v[4:5], s[0:1], v7, s10, v[6:7]
	v_mad_u64_u32 v[14:15], s[0:1], v43, s10, v[6:7]
	v_add3_u32 v13, 32, v2, v55
	s_add_u32 s2, s54, s2
	v_mad_u64_u32 v[10:11], s[0:1], v41, s10, v[6:7]
	v_mad_u64_u32 v[16:17], s[0:1], v9, s10, v[6:7]
	v_mad_u64_u32 v[18:19], s[0:1], v44, s10, v[6:7]
	v_mad_u64_u32 v[20:21], s[0:1], v45, s10, v[6:7]
	v_mad_u64_u32 v[22:23], s[0:1], v46, s10, v[6:7]
	v_mad_u64_u32 v[24:25], s[0:1], v47, s10, v[6:7]
	v_mad_u64_u32 v[26:27], s[0:1], v48, s10, v[6:7]
	v_mad_u64_u32 v[28:29], s[0:1], v49, s10, v[6:7]
	v_mad_u64_u32 v[30:31], s[0:1], v50, s10, v[6:7]
	v_mad_u64_u32 v[32:33], s[0:1], v51, s10, v[6:7]
	v_mad_u64_u32 v[34:35], s[0:1], v52, s10, v[6:7]
	v_mad_u64_u32 v[36:37], s[0:1], v53, s10, v[6:7]
	v_mad_u64_u32 v[6:7], s[0:1], v54, s10, v[6:7]
	v_add_u32_e32 v15, 0x400, v13
	s_waitcnt vmcnt(15)
	ds_write_b32 v4, v56
	s_waitcnt vmcnt(14)
	ds_write_b32 v10, v57
	s_waitcnt vmcnt(13)
	ds_write_b32 v12, v58
	s_waitcnt vmcnt(12)
	ds_write_b32 v14, v59
	s_waitcnt vmcnt(11)
	ds_write_b32 v16, v60
	s_waitcnt vmcnt(10)
	ds_write_b32 v18, v61
	s_waitcnt vmcnt(9)
	ds_write_b32 v20, v62
	s_waitcnt vmcnt(8)
	ds_write_b32 v22, v63
	s_waitcnt vmcnt(7)
	ds_write_b32 v24, v64
	s_waitcnt vmcnt(6)
	ds_write_b32 v26, v65
	s_waitcnt vmcnt(5)
	ds_write_b32 v28, v66
	s_waitcnt vmcnt(4)
	ds_write_b32 v30, v67
	s_waitcnt vmcnt(3)
	ds_write_b32 v32, v68
	s_waitcnt vmcnt(2)
	ds_write_b32 v34, v69
	s_waitcnt vmcnt(1)
	ds_write_b32 v36, v70
	s_waitcnt vmcnt(0)
	ds_write_b32 v6, v71
	s_waitcnt lgkmcnt(0)
	s_barrier
	ds_read2_b32 v[4:5], v13 offset1:129
	s_addc_u32 s3, s55, s3
	v_ashrrev_i32_e32 v9, 31, v8
	v_add_u32_e32 v17, 0x800, v13
	v_lshlrev_b32_e32 v2, 1, v1
	s_waitcnt lgkmcnt(0)
	v_cvt_pk_bf16_f32 v4, v4, v5
	ds_read2_b32 v[6:7], v15 offset0:2 offset1:131
	v_add_u32_e32 v38, 64, v8
	v_lshlrev_b64 v[8:9], 11, v[8:9]
	v_add_u32_e32 v19, 0xc00, v13
	v_lshl_add_u64 v[42:43], s[2:3], 0, v[2:3]
	s_waitcnt lgkmcnt(0)
	v_cvt_pk_bf16_f32 v5, v6, v7
	ds_read2_b32 v[6:7], v17 offset0:4 offset1:133
	v_ashrrev_i32_e32 v39, 31, v38
	v_lshl_add_u64 v[8:9], v[42:43], 0, v[8:9]
	s_waitcnt lgkmcnt(0)
	v_cvt_pk_bf16_f32 v6, v6, v7
	ds_read2_b32 v[10:11], v19 offset0:6 offset1:135
	s_waitcnt lgkmcnt(0)
	v_cvt_pk_bf16_f32 v7, v10, v11
	s_add_i32 s12, s12, s46
	s_add_i32 s7, s7, s8
	s_add_i32 s11, s11, s9
	v_lshlrev_b64 v[38:39], 11, v[38:39]
	ds_read2_b32 v[10:11], v13 offset0:64 offset1:193
	global_store_dwordx4 v[8:9], v[4:7], off
	s_cmpk_lt_i32 s12, 0x80
	s_waitcnt lgkmcnt(0)
	v_cvt_pk_bf16_f32 v4, v10, v11
	ds_read2_b32 v[6:7], v15 offset0:66 offset1:195
	s_waitcnt lgkmcnt(0)
	v_cvt_pk_bf16_f32 v5, v6, v7
	ds_read2_b32 v[6:7], v17 offset0:68 offset1:197
	v_lshl_add_u64 v[10:11], v[42:43], 0, v[38:39]
	s_waitcnt lgkmcnt(0)
	v_cvt_pk_bf16_f32 v6, v6, v7
	ds_read2_b32 v[8:9], v19 offset0:70 offset1:199
	s_waitcnt lgkmcnt(0)
	v_cvt_pk_bf16_f32 v7, v8, v9
	global_store_dwordx4 v[10:11], v[4:7], off
	s_barrier
	s_cbranch_scc1 .LBB0_373
.LBB0_374:
	s_waitcnt vmcnt(0)
	s_waitcnt lgkmcnt(0)
	s_barrier
	v_readfirstlane_b32 s2, v0
	s_lshr_b32 s2, s2, 6
	s_cmp_lg_u32 s2, 1
	s_cbranch_scc1 .LFB_b0_noinv
	buffer_inv sc1
	s_waitcnt vmcnt(0)
.LFB_b0_noinv:
	s_mov_b64 s[0:1], exec
	v_readlane_b32 s2, v244, 4
	v_readlane_b32 s3, v244, 5
	s_and_b64 s[2:3], s[0:1], s[2:3]
	s_mov_b64 exec, s[2:3]
	s_cbranch_execz .LBB0_426
	v_mov_b32_e32 v17, 0
	s_waitcnt vmcnt(0) expcnt(0) lgkmcnt(0)
	ds_read_b32 v3, v17 offset:16
	ds_read_b32 v1, v17 offset:20
	s_waitcnt lgkmcnt(1)
	v_cmp_ne_u32_e32 vcc, 0, v3
	s_cbranch_vccnz .LBB0_390
	v_readlane_b32 s2, v244, 6
	v_readlane_b32 s3, v244, 7
	s_load_dwordx2 s[10:11], s[2:3], 0x4
	s_add_u32 s2, s96, 0x1000
	s_addc_u32 s3, s97, 0
	s_add_u32 s8, s96, 0x1100
	s_addc_u32 s9, s97, 0
	s_waitcnt lgkmcnt(0)
	s_mul_i32 s7, s10, s46
	s_add_u32 s10, s96, 0x1200
	s_mul_i32 s7, s7, s11
	s_addc_u32 s11, s97, 0
	s_add_u32 s12, s96, 0x1300
	s_addc_u32 s13, s97, 0
	s_mov_b32 s20, 1
	s_branch .LBB0_378

.LBB0_390:
	s_lshl_b32 s7, s4, 8
	s_add_u32 s8, s96, s7
	s_addc_u32 s9, s97, 0
	v_mov_b32_e32 v4, 1
	v_mov_b32_e32 v2, 0x1000
	s_mov_b32 s10, 0
	s_nop 0
	global_atomic_add v4, v2, v4, s[8:9] offset:1024 sc0
	s_waitcnt vmcnt(0) lgkmcnt(0)
	v_add_u32_e32 v4, 1, v4
	v_cmp_ne_u32_e32 vcc, v4, v3
	s_cbranch_vccnz .LFB_b0_poll
	buffer_wbl2 sc1
	s_waitcnt vmcnt(0)
	s_mov_b64 s[2:3], exec
	s_mov_b64 exec, 0xffff
	v_mbcnt_lo_u32_b32 v5, -1, 0
	v_mov_b32_e32 v6, 1
	v_lshlrev_b32_e32 v5, 8, v5
	v_add_u32_e32 v5, 0x3640, v5
	global_atomic_add v5, v6, s[96:97]
	s_mov_b64 exec, s[2:3]
.LFB_b0_poll:
	v_mov_b32_e32 v2, 0x3000
	global_load_dword v248, v2, s[8:9] offset:1600 sc1
	s_sleep 3
	global_load_dword v249, v2, s[8:9] offset:1600 sc1
	s_sleep 3
	global_load_dword v250, v2, s[8:9] offset:1600 sc1
	s_sleep 3
	global_load_dword v251, v2, s[8:9] offset:1600 sc1
.LFB_b0_poll2:
	s_waitcnt vmcnt(3)
	v_cmp_ge_u32_e32 vcc, v248, v1
	s_cbranch_vccnz .LFB_b0_done
	global_load_dword v248, v2, s[8:9] offset:1600 sc1
	s_waitcnt vmcnt(3)
	v_cmp_ge_u32_e32 vcc, v249, v1
	s_cbranch_vccnz .LFB_b0_done
	global_load_dword v249, v2, s[8:9] offset:1600 sc1
	s_waitcnt vmcnt(3)
	v_cmp_ge_u32_e32 vcc, v250, v1
	s_cbranch_vccnz .LFB_b0_done
	global_load_dword v250, v2, s[8:9] offset:1600 sc1
	s_waitcnt vmcnt(3)
	v_cmp_ge_u32_e32 vcc, v251, v1
	s_cbranch_vccnz .LFB_b0_done
	global_load_dword v251, v2, s[8:9] offset:1600 sc1
	s_add_i32 s10, s10, 1
	s_cmp_lt_u32 s10, 0x10000
	s_cbranch_scc1 .LFB_b0_poll2
.LFB_b0_done:
.LBB0_426:
	s_or_b64 exec, exec, s[0:1]
	s_waitcnt lgkmcnt(0)
	s_barrier
	s_mov_b64 s[2:3], exec
	v_readlane_b32 s0, v244, 4
	v_readlane_b32 s1, v244, 5
	s_and_b64 s[0:1], s[2:3], s[0:1]
	s_mov_b64 exec, s[0:1]
	s_cbranch_execz .LBB0_428
	v_mov_b32_e32 v1, 0x3000
	s_getreg_b32 s0, hwreg(HW_REG_XCC_ID, 0, 4)
	global_load_dword v2, v1, s[96:97] offset:1536 sc1
	global_load_dword v3, v1, s[96:97] offset:1792 sc1
	global_load_dword v4, v1, s[96:97] offset:2048 sc1
	global_load_dword v5, v1, s[96:97] offset:2304 sc1
	global_load_dword v6, v1, s[96:97] offset:2560 sc1
	global_load_dword v7, v1, s[96:97] offset:2816 sc1
	global_load_dword v8, v1, s[96:97] offset:3072 sc1
	global_load_dword v9, v1, s[96:97] offset:3328 sc1
	global_load_dword v10, v1, s[96:97] offset:3584 sc1
	s_nop 0
	global_load_dword v1, v1, s[96:97] offset:3840 sc1
	v_mov_b32_e32 v11, 0x4000
	global_load_dword v12, v11, s[96:97] sc1
	global_load_dword v13, v11, s[96:97] offset:256 sc1
	global_load_dword v14, v11, s[96:97] offset:512 sc1
	global_load_dword v15, v11, s[96:97] offset:768 sc1
	global_load_dword v16, v11, s[96:97] offset:1024 sc1
	s_nop 0
	global_load_dword v11, v11, s[96:97] offset:1280 sc1
	s_and_b32 s7, s0, 15
	s_cmp_eq_u32 s7, 0
	s_cselect_b64 vcc, -1, 0
	s_cmp_gt_u32 s7, 1
	s_cselect_b64 s[0:1], -1, 0
	s_cmp_eq_u32 s7, 1
	s_waitcnt vmcnt(15)
	v_cndmask_b32_e64 v17, v2, 0, vcc
	v_cndmask_b32_e32 v2, 1, v2, vcc
	s_cselect_b64 vcc, -1, 0
	s_cmp_gt_u32 s7, 2
	s_waitcnt vmcnt(14)
	v_cndmask_b32_e32 v2, v2, v3, vcc
	s_cselect_b64 vcc, -1, 0
	s_cmp_eq_u32 s7, 2
	v_cndmask_b32_e64 v18, 0, v3, s[0:1]
	s_waitcnt vmcnt(13)
	v_cndmask_b32_e32 v3, 0, v4, vcc
	s_cselect_b64 vcc, -1, 0
	s_cmp_gt_u32 s7, 3
	v_cndmask_b32_e32 v2, v2, v4, vcc
	s_cselect_b64 vcc, -1, 0
	s_cmp_eq_u32 s7, 3
	v_add_u32_e32 v17, v18, v17
	s_waitcnt vmcnt(12)
	v_cndmask_b32_e32 v4, 0, v5, vcc
	s_cselect_b64 vcc, -1, 0
	s_cmp_gt_u32 s7, 4
	v_add_u32_e32 v3, v3, v17
	v_cndmask_b32_e32 v2, v2, v5, vcc
	s_cselect_b64 vcc, -1, 0
	s_cmp_eq_u32 s7, 4
	v_add_u32_e32 v3, v4, v3
	s_waitcnt vmcnt(11)
	v_cndmask_b32_e32 v4, 0, v6, vcc
	s_cselect_b64 vcc, -1, 0
	s_cmp_gt_u32 s7, 5
	v_cndmask_b32_e32 v2, v2, v6, vcc
	s_cselect_b64 vcc, -1, 0
	s_cmp_eq_u32 s7, 5
	v_add_u32_e32 v3, v4, v3
	s_waitcnt vmcnt(10)
	v_cndmask_b32_e32 v4, 0, v7, vcc
	s_cselect_b64 vcc, -1, 0
	s_cmp_gt_u32 s7, 6
	v_cndmask_b32_e32 v2, v2, v7, vcc
	s_cselect_b64 vcc, -1, 0
	s_cmp_eq_u32 s7, 6
	v_add_u32_e32 v3, v4, v3
	s_waitcnt vmcnt(9)
	v_cndmask_b32_e32 v4, 0, v8, vcc
	s_cselect_b64 vcc, -1, 0
	s_cmp_gt_u32 s7, 7
	v_cndmask_b32_e32 v2, v2, v8, vcc
	s_cselect_b64 vcc, -1, 0
	s_cmp_eq_u32 s7, 7
	v_add_u32_e32 v3, v4, v3
	s_waitcnt vmcnt(8)
	v_cndmask_b32_e32 v4, 0, v9, vcc
	s_cselect_b64 vcc, -1, 0
	s_cmp_gt_u32 s7, 8
	v_cndmask_b32_e32 v2, v2, v9, vcc
	s_cselect_b64 vcc, -1, 0
	s_cmp_eq_u32 s7, 8
	v_add_u32_e32 v3, v4, v3
	s_waitcnt vmcnt(7)
	v_cndmask_b32_e32 v4, 0, v10, vcc
	s_cselect_b64 vcc, -1, 0
	s_cmp_gt_u32 s7, 9
	v_cndmask_b32_e32 v2, v2, v10, vcc
	s_cselect_b64 vcc, -1, 0
	s_cmp_eq_u32 s7, 9
	v_add_u32_e32 v3, v4, v3
	s_waitcnt vmcnt(6)
	v_cndmask_b32_e32 v4, 0, v1, vcc
	s_cselect_b64 vcc, -1, 0
	s_cmp_gt_u32 s7, 10
	v_cndmask_b32_e32 v1, v2, v1, vcc
	s_cselect_b64 vcc, -1, 0
	s_cmp_eq_u32 s7, 10
	s_waitcnt vmcnt(5)
	v_cndmask_b32_e32 v2, 0, v12, vcc
	s_cselect_b64 vcc, -1, 0
	s_cmp_gt_u32 s7, 11
	v_add_u32_e32 v3, v4, v3
	v_cndmask_b32_e32 v1, v1, v12, vcc
	s_cselect_b64 vcc, -1, 0
	s_cmp_eq_u32 s7, 11
	v_add_u32_e32 v2, v2, v3
	s_waitcnt vmcnt(4)
	v_cndmask_b32_e32 v3, 0, v13, vcc
	s_cselect_b64 vcc, -1, 0
	s_cmp_gt_u32 s7, 12
	v_cndmask_b32_e32 v1, v1, v13, vcc
	s_cselect_b64 vcc, -1, 0
	s_cmp_eq_u32 s7, 12
	v_add_u32_e32 v2, v3, v2
	s_waitcnt vmcnt(3)
	v_cndmask_b32_e32 v3, 0, v14, vcc
	s_cselect_b64 vcc, -1, 0
	s_cmp_gt_u32 s7, 13
	v_cndmask_b32_e32 v1, v1, v14, vcc
	s_cselect_b64 vcc, -1, 0
	s_cmp_eq_u32 s7, 13
	v_add_u32_e32 v2, v3, v2
	s_waitcnt vmcnt(2)
	v_cndmask_b32_e32 v3, 0, v15, vcc
	s_cselect_b64 vcc, -1, 0
	s_cmp_eq_u32 s7, 14
	v_cndmask_b32_e32 v1, v1, v15, vcc
	s_cselect_b64 vcc, -1, 0
	s_cmp_eq_u32 s7, 15
	s_waitcnt vmcnt(1)
	v_cndmask_b32_e32 v1, v1, v16, vcc
	s_cselect_b64 vcc, -1, 0
	v_add_u32_e32 v2, v3, v2
	v_cndmask_b32_e32 v3, 0, v16, vcc
	s_waitcnt vmcnt(0)
	v_cndmask_b32_e32 v1, v1, v11, vcc
	v_add_u32_e32 v2, v3, v2
	v_mov_b32_e32 v3, 0
	ds_write_b32 v3, v1 offset:4
	ds_write_b32 v3, v2 offset:8

.LFB_b1_noinv:
	s_mov_b64 s[0:1], exec
	v_readlane_b32 s2, v244, 4
	v_readlane_b32 s3, v244, 5
	s_and_b64 s[2:3], s[0:1], s[2:3]
	s_mov_b64 exec, s[2:3]
	s_cbranch_execz .LBB0_717
	v_readlane_b32 s4, v243, 10
	v_readlane_b32 s5, v243, 11
	v_readlane_b32 s2, v242, 40
	s_waitcnt vmcnt(0) expcnt(0) lgkmcnt(0)
	ds_read_b32 v4, v155 offset:16
	ds_read_b32 v2, v155 offset:20
	v_mov_b32_e32 v5, 1
	s_mul_i32 s2, s2, 3
	s_add_i32 s3, s2, 2
	s_add_i32 s2, s2, 1
	global_atomic_add v5, v155, v5, s[4:5] sc0
	s_add_u32 s6, s4, 0x2240
	s_addc_u32 s7, s5, 0
	s_mov_b32 s10, 0
	s_waitcnt lgkmcnt(0)
	v_mul_lo_u32 v6, v4, s3
	v_mul_lo_u32 v7, v2, s3
	s_waitcnt vmcnt(0)
	v_add_u32_e32 v5, 1, v5
	v_cmp_ne_u32_e32 vcc, v5, v6
	s_cbranch_vccnz .LFB_b1_poll
	s_mov_b64 s[12:13], exec
	s_mov_b64 exec, 0xffff
	v_mbcnt_lo_u32_b32 v8, -1, 0
	v_mov_b32_e32 v9, 1
	v_lshlrev_b32_e32 v8, 8, v8
	v_add_u32_e32 v8, 0x3640, v8
	global_atomic_add v8, v9, s[96:97]
	s_mov_b64 exec, s[12:13]
.LFB_b1_poll:
	global_load_dword v248, v155, s[6:7] sc1
	s_sleep 3
	global_load_dword v249, v155, s[6:7] sc1
	s_sleep 3
	global_load_dword v250, v155, s[6:7] sc1
	s_sleep 3
	global_load_dword v251, v155, s[6:7] sc1
.LFB_b1_poll2:
	s_waitcnt vmcnt(3)
	v_cmp_ge_u32_e32 vcc, v248, v7
	s_cbranch_vccnz .LFB_b1_done
	global_load_dword v248, v155, s[6:7] sc1
	s_waitcnt vmcnt(3)
	v_cmp_ge_u32_e32 vcc, v249, v7
	s_cbranch_vccnz .LFB_b1_done
	global_load_dword v249, v155, s[6:7] sc1
	s_waitcnt vmcnt(3)
	v_cmp_ge_u32_e32 vcc, v250, v7
	s_cbranch_vccnz .LFB_b1_done
	global_load_dword v250, v155, s[6:7] sc1
	s_waitcnt vmcnt(3)
	v_cmp_ge_u32_e32 vcc, v251, v7
	s_cbranch_vccnz .LFB_b1_done
	global_load_dword v251, v155, s[6:7] sc1
	s_add_i32 s10, s10, 1
	s_cmp_lt_u32 s10, 0x10000
	s_cbranch_scc1 .LFB_b1_poll2
.LFB_b1_done:
.LBB0_717:
	s_or_b64 exec, exec, s[0:1]
	v_readlane_b32 s0, v243, 22
	v_readlane_b32 s1, v243, 23
	s_andn2_b64 vcc, exec, s[0:1]
	s_waitcnt lgkmcnt(0)
	s_barrier
	s_cbranch_vccnz .LBB0_743
	v_mov_b32_e32 v2, v0
	s_movk_i32 s0, 0xba0
	v_mov_b32_e32 v70, 0
	v_cmp_gt_i32_e32 vcc, s0, v2
	v_mov_b32_e32 v66, 0
	v_mov_b32_e32 v67, 0
	v_mov_b32_e32 v68, 0
	v_mov_b32_e32 v69, 0
	s_and_saveexec_b64 s[0:1], vcc
	s_cbranch_execz .LBB0_722
	s_mov_b32 s2, 0x2aaaaaab
	v_mul_hi_i32 v3, v2, s2
	v_lshrrev_b32_e32 v4, 31, v3
	v_ashrrev_i32_e32 v3, 3, v3
	v_add_u32_e32 v3, v3, v4
	v_subrev_u32_e32 v4, 30, v3
	v_readlane_b32 s2, v243, 24
	v_mov_b32_e32 v69, 0
	v_mov_b32_e32 v68, 0
	v_cmp_lt_i32_e32 vcc, s2, v4
	v_mov_b32_e32 v67, 0
	v_mov_b32_e32 v66, 0
	s_and_saveexec_b64 s[2:3], vcc
	s_cbranch_execz .LBB0_721
	v_readlane_b32 s4, v243, 25
	s_nop 1
	v_add_u32_e32 v4, s4, v4
	s_movk_i32 s4, 0xffd0
	v_ashrrev_i32_e32 v5, 31, v4
	v_mul_lo_u32 v3, v3, s4
	v_lshlrev_b64 v[4:5], 12, v[4:5]
	v_add_lshl_u32 v6, v3, v2, 3
	v_lshl_add_u64 v[4:5], s[60:61], 0, v[4:5]
	v_ashrrev_i32_e32 v7, 31, v6
	v_lshl_add_u64 v[4:5], v[6:7], 1, v[4:5]
	global_load_dwordx4 v[66:69], v[4:5], off

.LFB_b2_noinv:
	s_mov_b64 s[0:1], exec
	v_readlane_b32 s2, v244, 4
	v_readlane_b32 s3, v244, 5
	s_and_b64 s[2:3], s[0:1], s[2:3]
	s_mov_b64 exec, s[2:3]
	s_cbranch_execz .LBB0_915
	v_readlane_b32 s4, v243, 10
	v_readlane_b32 s5, v243, 11
	v_readlane_b32 s2, v242, 40
	s_waitcnt vmcnt(0) expcnt(0) lgkmcnt(0)
	ds_read_b32 v4, v155 offset:16
	ds_read_b32 v2, v155 offset:20
	v_mov_b32_e32 v5, 1
	s_mul_i32 s2, s2, 3
	s_add_i32 s3, s2, 3
	s_add_i32 s2, s2, 2
	global_atomic_add v5, v155, v5, s[4:5] sc0
	s_add_u32 s6, s4, 0x2240
	s_addc_u32 s7, s5, 0
	s_mov_b32 s10, 0
	s_waitcnt lgkmcnt(0)
	v_mul_lo_u32 v6, v4, s3
	v_mul_lo_u32 v7, v2, s3
	s_waitcnt vmcnt(0)
	v_add_u32_e32 v5, 1, v5
	v_cmp_ne_u32_e32 vcc, v5, v6
	s_cbranch_vccnz .LFB_b2_poll
	buffer_wbl2 sc1
	s_waitcnt vmcnt(0)
	s_mov_b64 s[12:13], exec
	s_mov_b64 exec, 0xffff
	v_mbcnt_lo_u32_b32 v8, -1, 0
	v_mov_b32_e32 v9, 1
	v_lshlrev_b32_e32 v8, 8, v8
	v_add_u32_e32 v8, 0x3640, v8
	global_atomic_add v8, v9, s[96:97]
	s_mov_b64 exec, s[12:13]

.LFB_b2_done:
.LBB0_915:
	s_or_b64 exec, exec, s[0:1]
	v_readlane_b32 s2, v244, 9
	v_readlane_b32 s3, v244, 10
	s_andn2_b64 vcc, exec, s[2:3]
	s_mov_b64 s[0:1], -1
	s_waitcnt vmcnt(0) lgkmcnt(0)
	v_cndmask_b32_e64 v2, 0, 1, s[2:3]
	v_readlane_b32 s2, v242, 0
	v_readlane_b32 s2, v242, 40
	v_readlane_b32 s3, v242, 1
	s_mulk_i32 s2, 0x4200
	v_cmp_ne_u32_e64 s[12:13], 1, v2
	v_writelane_b32 v242, s2, 0
	s_barrier
	s_nop 0
	v_writelane_b32 v242, s3, 1
	s_cbranch_vccnz .LBB0_917
	s_mov_b64 s[0:1], 0

.LFB_b3_noinv:
	s_mov_b64 s[0:1], exec
	v_readlane_b32 s2, v244, 4
	v_readlane_b32 s3, v244, 5
	s_and_b64 s[2:3], s[0:1], s[2:3]
	s_mov_b64 exec, s[2:3]
	s_cbranch_execz .LBB0_430
	v_readlane_b32 s4, v243, 10
	v_readlane_b32 s5, v243, 11
	v_readlane_b32 s2, v242, 40
	s_waitcnt vmcnt(0) expcnt(0) lgkmcnt(0)
	ds_read_b32 v4, v155 offset:16
	ds_read_b32 v2, v155 offset:20
	v_mov_b32_e32 v5, 1
	s_mul_i32 s2, s2, 3
	s_add_i32 s3, s2, 4
	s_add_i32 s2, s2, 3
	global_atomic_add v5, v155, v5, s[4:5] sc0
	s_add_u32 s6, s4, 0x2240
	s_addc_u32 s7, s5, 0
	s_mov_b32 s10, 0
	s_waitcnt lgkmcnt(0)
	v_mul_lo_u32 v6, v4, s3
	v_mul_lo_u32 v7, v2, s3
	s_waitcnt vmcnt(0)
	v_add_u32_e32 v5, 1, v5
	v_cmp_ne_u32_e32 vcc, v5, v6
	s_cbranch_vccnz .LFB_b3_poll
	s_mov_b64 s[12:13], exec
	s_mov_b64 exec, 0xffff
	v_mbcnt_lo_u32_b32 v8, -1, 0
	v_mov_b32_e32 v9, 1
	v_lshlrev_b32_e32 v8, 8, v8
	v_add_u32_e32 v8, 0x3640, v8
	global_atomic_add v8, v9, s[96:97]
	s_mov_b64 exec, s[12:13]

.LFB_b3_done:
	s_branch .LBB0_430
.LBB0_1012:
	v_readlane_b32 s0, v244, 8
	s_nop 1
	v_add_u32_e32 v2, s0, v0
	s_mov_b32 s0, 0x210000
	v_cmp_gt_i32_e32 vcc, s0, v2
	s_and_saveexec_b64 s[0:1], vcc
	s_cbranch_execz .LBB0_1015
	v_readlane_b32 s0, v244, 0
	v_readlane_b32 s1, v244, 1
	v_readlane_b32 s2, v244, 2
	v_readlane_b32 s3, v244, 3
	s_add_u32 s0, s0, 0x21000
	v_lshlrev_b32_e32 v0, 3, v0
	s_addc_u32 s1, s1, 0
	s_lshl_b32 s4, s46, 9
	v_lshl_add_u32 v3, s24, 12, v0
	s_lshl_b32 s5, s46, 12
	s_mov_b64 s[2:3], 0
	v_mov_b32_e32 v1, 0
	v_mov_b32_e32 v4, 0x358637bd
	s_mov_b32 s6, 0x800000
	s_mov_b32 s7, 0x20ffff

	.amdhsa_kernel _Z14fwd_megakernel6Params
		.amdhsa_group_segment_fixed_size 32
		.amdhsa_private_segment_fixed_size 0
		.amdhsa_kernarg_size 472
		.amdhsa_user_sgpr_count 2
		.amdhsa_user_sgpr_dispatch_ptr 0
		.amdhsa_user_sgpr_queue_ptr 0
		.amdhsa_user_sgpr_kernarg_segment_ptr 1
		.amdhsa_user_sgpr_dispatch_id 0
		.amdhsa_user_sgpr_kernarg_preload_length 0
		.amdhsa_user_sgpr_kernarg_preload_offset 0
		.amdhsa_user_sgpr_private_segment_size 0
		.amdhsa_uses_dynamic_stack 0
		.amdhsa_enable_private_segment 0
		.amdhsa_system_sgpr_workgroup_id_x 1
		.amdhsa_system_sgpr_workgroup_id_y 0
		.amdhsa_system_sgpr_workgroup_id_z 0
		.amdhsa_system_sgpr_workgroup_info 0
		.amdhsa_system_vgpr_workitem_id 0
		.amdhsa_next_free_vgpr 256
		.amdhsa_next_free_sgpr 102
		.amdhsa_accum_offset 256
		.amdhsa_reserve_vcc 1
		.amdhsa_float_round_mode_32 0
		.amdhsa_float_round_mode_16_64 0
		.amdhsa_float_denorm_mode_32 3
		.amdhsa_float_denorm_mode_16_64 3
		.amdhsa_dx10_clamp 1
		.amdhsa_ieee_mode 1
		.amdhsa_fp16_overflow 0
		.amdhsa_tg_split 0
		.amdhsa_exception_fp_ieee_invalid_op 0
		.amdhsa_exception_fp_denorm_src 0
		.amdhsa_exception_fp_ieee_div_zero 0
		.amdhsa_exception_fp_ieee_overflow 0
		.amdhsa_exception_fp_ieee_underflow 0
		.amdhsa_exception_fp_ieee_inexact 0
		.amdhsa_exception_int_div_zero 0
	.end_amdhsa_kernel

amdhsa.kernels:
  - .agpr_count:     0
    .args:
      - .offset:         0
        .size:           216
        .value_kind:     by_value
      - .offset:         216
        .size:           4
        .value_kind:     hidden_block_count_x
      - .offset:         220
        .size:           4
        .value_kind:     hidden_block_count_y
      - .offset:         224
        .size:           4
        .value_kind:     hidden_block_count_z
      - .offset:         228
        .size:           2
        .value_kind:     hidden_group_size_x
      - .offset:         230
        .size:           2
        .value_kind:     hidden_group_size_y
      - .offset:         232
        .size:           2
        .value_kind:     hidden_group_size_z
      - .offset:         234
        .size:           2
        .value_kind:     hidden_remainder_x
      - .offset:         236
        .size:           2
        .value_kind:     hidden_remainder_y
      - .offset:         238
        .size:           2
        .value_kind:     hidden_remainder_z
      - .offset:         256
        .size:           8
        .value_kind:     hidden_global_offset_x
      - .offset:         264
        .size:           8
        .value_kind:     hidden_global_offset_y
      - .offset:         272
        .size:           8
        .value_kind:     hidden_global_offset_z
      - .offset:         280
        .size:           2
        .value_kind:     hidden_grid_dims
      - .offset:         336
        .size:           4
        .value_kind:     hidden_dynamic_lds_size
    .group_segment_fixed_size: 32
    .kernarg_segment_align: 8
    .kernarg_segment_size: 472
    .language:       OpenCL C
    .language_version:
      - 2
      - 0
    .max_flat_workgroup_size: 512
    .name:           _Z14fwd_megakernel6Params
    .private_segment_fixed_size: 0
    .sgpr_count:     108
    .sgpr_spill_count: 192
    .symbol:         _Z14fwd_megakernel6Params.kd
    .uniform_work_group_size: 1
    .uses_dynamic_stack: false
    .vgpr_count:     256
    .vgpr_spill_count: 0
    .wavefront_size: 64
